# ln_router L1 router GEMV also uses packed-f32 dot products with pipelined LDS reads
# speedup vs baseline: 1.0057x; 1.0011x over previous
.LBB0_1871:
	s_or_b64 exec, exec, s[2:3]
	v_add_u32_e32 v33, 0xfffff000, v32
	v_lshrrev_b32_e32 v33, 11, v33
	v_add_u32_e32 v33, 4, v33
	v_cndmask_b32_e32 v33, 3, v33, vcc
	v_mad_u64_u32 v[74:75], s[2:3], v33, s31, v[60:61]
	v_lshl_add_u64 v[90:91], v[74:75], 0, s[26:27]
	v_lshl_add_u64 v[92:93], v[74:75], 0, s[28:29]
	v_lshl_add_u64 v[82:83], v[90:91], 0, v[34:35]
	v_lshl_add_u64 v[86:87], v[92:93], 0, v[34:35]
	global_load_dwordx4 v[74:77], v[38:39], off
	global_load_dwordx4 v[78:81], v[40:41], off
	s_nop 0
	global_load_dwordx4 v[82:85], v[82:83], off
	s_nop 0
	global_load_dwordx4 v[86:89], v[86:87], off
	v_add_f32_e32 v69, v28, v29
	v_add_f32_e32 v33, v69, v30
	v_add_f32_e32 v69, v24, v25
	v_add_f32_e32 v33, v33, v31
	v_add_f32_e32 v69, v69, v26
	v_add_f32_e32 v33, 0, v33
	v_add_f32_e32 v69, v69, v27
	v_add_f32_e32 v33, v33, v69
	v_add_f32_e32 v69, v20, v21
	v_add_f32_e32 v69, v69, v22
	v_add_f32_e32 v69, v69, v23
	v_add_f32_e32 v33, v33, v69
	v_add_f32_e32 v69, v16, v17
	v_add_f32_e32 v69, v69, v18
	v_add_f32_e32 v69, v69, v19
	v_pk_mul_f32 v[94:95], v[28:29], v[28:29]
	v_pk_mul_f32 v[98:99], v[24:25], v[24:25]
	v_add_f32_e32 v33, v33, v69
	v_pk_mul_f32 v[96:97], v[30:31], v[30:31]
	v_pk_mul_f32 v[100:101], v[26:27], v[26:27]
	v_add_f32_e32 v69, v98, v99
	v_add_f32_e32 v94, v94, v95
	v_add_f32_e32 v69, v69, v100
	v_add_f32_e32 v94, v94, v96
	v_pk_mul_f32 v[102:103], v[20:21], v[20:21]
	v_add_f32_e32 v69, v69, v101
	v_add_f32_e32 v94, v94, v97
	v_pk_mul_f32 v[104:105], v[22:23], v[22:23]
	v_add_f32_e32 v69, v94, v69
	v_add_f32_e32 v94, v102, v103
	v_add_f32_e32 v94, v94, v104
	v_pk_mul_f32 v[106:107], v[16:17], v[16:17]
	v_add_f32_e32 v94, v94, v105
	v_pk_mul_f32 v[108:109], v[18:19], v[18:19]
	v_add_f32_e32 v69, v69, v94
	v_add_f32_e32 v94, v106, v107
	v_add_f32_e32 v94, v94, v108
	v_add_f32_e32 v94, v94, v109
	v_add_f32_dpp v33, v33, v33 row_ror:8 row_mask:0xf bank_mask:0xf bound_ctrl:1
	v_add_f32_e32 v69, v69, v94
	s_nop 0
	v_add_f32_dpp v33, v33, v33 row_ror:4 row_mask:0xf bank_mask:0xf bound_ctrl:1
	v_add_f32_dpp v69, v69, v69 row_ror:8 row_mask:0xf bank_mask:0xf bound_ctrl:1
	s_nop 0
	v_add_f32_dpp v33, v33, v33 row_ror:2 row_mask:0xf bank_mask:0xf bound_ctrl:1
	v_add_f32_dpp v69, v69, v69 row_ror:4 row_mask:0xf bank_mask:0xf bound_ctrl:1
	s_nop 0
	v_add_f32_dpp v33, v33, v33 row_ror:1 row_mask:0xf bank_mask:0xf bound_ctrl:1
	v_add_f32_dpp v69, v69, v69 row_ror:2 row_mask:0xf bank_mask:0xf bound_ctrl:1
	v_mov_b32_e32 v94, v33
	s_nop 1
	v_permlane16_swap_b32_e32 v33, v94
	v_add_f32_dpp v69, v69, v69 row_ror:1 row_mask:0xf bank_mask:0xf bound_ctrl:1
	v_add_f32_e32 v95, v33, v94
	v_mov_b32_e32 v33, v69
	s_nop 1
	v_permlane16_swap_b32_e32 v69, v33
	v_add_f32_e32 v94, v69, v33
	v_mov_b32_e32 v97, v95
	v_mov_b32_e32 v96, v94
	s_nop 0
	v_permlane32_swap_b32_e32 v95, v97
	v_permlane32_swap_b32_e32 v94, v96
	v_pk_add_f32 v[94:95], v[94:95], v[96:97]
	s_nop 0
	v_pk_mul_f32 v[122:123], v[94:95], s[24:25] op_sel_hi:[1,0]
	s_nop 0
	v_fma_f32 v33, -v123, v123, v122
	v_max_f32_e32 v33, 0, v33
	v_add_f32_e32 v33, 0x3727c5ac, v33
	v_mul_f32_e32 v69, 0x4b800000, v33
	v_cmp_gt_f32_e32 vcc, s33, v33
	v_pk_add_f32 v[28:29], v[28:29], v[122:123] op_sel:[0,1] neg_lo:[0,1] neg_hi:[0,1]
	v_pk_add_f32 v[30:31], v[30:31], v[122:123] op_sel:[0,1] neg_lo:[0,1] neg_hi:[0,1]
	v_cndmask_b32_e32 v33, v33, v69, vcc
	v_rsq_f32_e32 v33, v33
	v_pk_add_f32 v[24:25], v[24:25], v[122:123] op_sel:[0,1] neg_lo:[0,1] neg_hi:[0,1]
	v_pk_add_f32 v[26:27], v[26:27], v[122:123] op_sel:[0,1] neg_lo:[0,1] neg_hi:[0,1]
	v_pk_add_f32 v[20:21], v[20:21], v[122:123] op_sel:[0,1] neg_lo:[0,1] neg_hi:[0,1]
	v_mul_f32_e32 v69, 0x45800000, v33
	v_cndmask_b32_e32 v124, v33, v69, vcc
	v_pk_mul_f32 v[28:29], v[28:29], v[124:125] op_sel_hi:[1,0]
	v_pk_mul_f32 v[30:31], v[30:31], v[124:125] op_sel_hi:[1,0]
	s_waitcnt vmcnt(2)
	v_pk_fma_f32 v[28:29], v[74:75], v[28:29], v[78:79]
	s_waitcnt vmcnt(0)
	v_pk_add_f32 v[74:75], v[86:87], 1.0 op_sel_hi:[1,0]
	v_ashrrev_i32_e32 v33, 31, v32
	v_pk_fma_f32 v[28:29], v[74:75], v[28:29], v[82:83]
	v_pk_fma_f32 v[30:31], v[76:77], v[30:31], v[80:81]
	v_pk_add_f32 v[74:75], v[88:89], 1.0 op_sel_hi:[1,0]
	v_lshlrev_b64 v[94:95], 11, v[32:33]
	v_pk_fma_f32 v[30:31], v[30:31], v[74:75], v[84:85]
	v_cvt_pk_bf16_f32 v74, v28, v29
	v_cvt_pk_bf16_f32 v75, v30, v31
	v_lshl_add_u64 v[126:127], v[58:59], 0, v[94:95]
	global_store_dwordx2 v[126:127], v[74:75], off
	v_lshl_add_u64 v[82:83], v[92:93], 0, v[62:63]
	global_load_dwordx4 v[74:77], v[42:43], off
	global_load_dwordx4 v[78:81], v[44:45], off
	s_nop 0
	global_load_dwordx4 v[82:85], v[82:83], off
	v_lshl_add_u64 v[86:87], v[90:91], 0, v[62:63]
	global_load_dwordx4 v[86:89], v[86:87], off
	v_pk_mul_f32 v[24:25], v[24:25], v[124:125] op_sel_hi:[1,0]
	v_pk_mul_f32 v[26:27], v[26:27], v[124:125] op_sel_hi:[1,0]
	v_lshl_add_u64 v[94:95], v[92:93], 0, v[64:65]
	v_pk_add_f32 v[22:23], v[22:23], v[122:123] op_sel:[0,1] neg_lo:[0,1] neg_hi:[0,1]
	v_pk_mul_f32 v[20:21], v[20:21], v[124:125] op_sel_hi:[1,0]
	v_pk_mul_f32 v[22:23], v[22:23], v[124:125] op_sel_hi:[1,0]
	v_lshl_add_u64 v[92:93], v[92:93], 0, v[66:67]
	v_pk_add_f32 v[16:17], v[16:17], v[122:123] op_sel:[0,1] neg_lo:[0,1] neg_hi:[0,1]
	v_pk_add_f32 v[18:19], v[18:19], v[122:123] op_sel:[0,1] neg_lo:[0,1] neg_hi:[0,1]
	v_pk_mul_f32 v[16:17], v[16:17], v[124:125] op_sel_hi:[1,0]
	v_pk_mul_f32 v[18:19], v[18:19], v[124:125] op_sel_hi:[1,0]
	s_waitcnt vmcnt(2)
	v_pk_fma_f32 v[24:25], v[24:25], v[74:75], v[78:79]
	s_waitcnt vmcnt(1)
	v_pk_add_f32 v[74:75], v[82:83], 1.0 op_sel_hi:[1,0]
	v_pk_fma_f32 v[76:77], v[26:27], v[76:77], v[80:81]
	v_pk_add_f32 v[78:79], v[84:85], 1.0 op_sel_hi:[1,0]
	s_waitcnt vmcnt(0)
	v_pk_fma_f32 v[26:27], v[24:25], v[74:75], v[86:87]
	v_pk_fma_f32 v[24:25], v[76:77], v[78:79], v[88:89]
	v_cvt_pk_bf16_f32 v74, v26, v27
	v_cvt_pk_bf16_f32 v75, v24, v25
	global_store_dwordx2 v[126:127], v[74:75], off offset:512
	global_load_dwordx4 v[74:77], v[46:47], off
	s_nop 0
	global_load_dwordx4 v[78:81], v[48:49], off
	global_load_dwordx4 v[82:85], v[94:95], off
	v_lshl_add_u64 v[86:87], v[90:91], 0, v[64:65]
	global_load_dwordx4 v[86:89], v[86:87], off
	s_waitcnt vmcnt(2)
	v_pk_fma_f32 v[20:21], v[20:21], v[74:75], v[78:79]
	s_waitcnt vmcnt(1)
	v_pk_add_f32 v[74:75], v[82:83], 1.0 op_sel_hi:[1,0]
	v_pk_fma_f32 v[76:77], v[22:23], v[76:77], v[80:81]
	v_pk_add_f32 v[78:79], v[84:85], 1.0 op_sel_hi:[1,0]
	s_waitcnt vmcnt(0)
	v_pk_fma_f32 v[22:23], v[20:21], v[74:75], v[86:87]
	v_pk_fma_f32 v[20:21], v[76:77], v[78:79], v[88:89]
	v_cvt_pk_bf16_f32 v74, v22, v23
	v_cvt_pk_bf16_f32 v75, v20, v21
	global_store_dwordx2 v[126:127], v[74:75], off offset:1024
	global_load_dwordx4 v[74:77], v[50:51], off
	s_nop 0
	global_load_dwordx4 v[78:81], v[52:53], off
	global_load_dwordx4 v[82:85], v[92:93], off
	v_lshl_add_u64 v[86:87], v[90:91], 0, v[66:67]
	global_load_dwordx4 v[86:89], v[86:87], off
	ds_read_b128 v[90:93], v36
	ds_read_b128 v[94:97], v36 offset:1024
	ds_read_b128 v[98:101], v36 offset:2048
	ds_read_b128 v[102:105], v36 offset:3072
	ds_read_b128 v[106:109], v36 offset:7168
	ds_read_b128 v[110:113], v36 offset:6144
	ds_read_b128 v[114:117], v36 offset:5120
	ds_read_b128 v[118:121], v36 offset:4096
	s_waitcnt lgkmcnt(7)
	v_mul_f32_e32 v69, v29, v91
	v_fmac_f32_e32 v69, v28, v90
	v_fmac_f32_e32 v69, v30, v92
	s_waitcnt lgkmcnt(1)
	v_mul_f32_e32 v92, v26, v114
	s_waitcnt lgkmcnt(0)
	v_mul_f32_e32 v91, v28, v118
	v_fmac_f32_e32 v91, v29, v119
	v_fmac_f32_e32 v91, v30, v120
	v_fmac_f32_e32 v91, v31, v121
	v_add_f32_e32 v90, 0, v91
	v_mul_f32_e32 v91, v27, v95
	v_fmac_f32_e32 v91, v26, v94
	v_fmac_f32_e32 v92, v27, v115
	v_fmac_f32_e32 v69, v31, v93
	v_fmac_f32_e32 v91, v24, v96
	v_fmac_f32_e32 v92, v24, v116
	v_add_f32_e32 v69, 0, v69
	v_fmac_f32_e32 v91, v25, v97
	v_fmac_f32_e32 v92, v25, v117
	v_add_f32_e32 v69, v69, v91
	v_add_f32_e32 v90, v92, v90
	v_mul_f32_e32 v91, v23, v99
	v_mul_f32_e32 v92, v22, v110
	v_fmac_f32_e32 v91, v22, v98
	v_fmac_f32_e32 v92, v23, v111
	v_fmac_f32_e32 v91, v20, v100
	v_fmac_f32_e32 v92, v20, v112
	v_fmac_f32_e32 v91, v21, v101
	v_fmac_f32_e32 v92, v21, v113
	v_add_f32_e32 v69, v69, v91
	v_add_f32_e32 v90, v92, v90
	s_waitcnt vmcnt(2)
	v_pk_fma_f32 v[16:17], v[16:17], v[74:75], v[78:79]
	s_waitcnt vmcnt(1)
	v_pk_add_f32 v[74:75], v[82:83], 1.0 op_sel_hi:[1,0]
	v_pk_fma_f32 v[76:77], v[18:19], v[76:77], v[80:81]
	v_pk_add_f32 v[78:79], v[84:85], 1.0 op_sel_hi:[1,0]
	s_waitcnt vmcnt(0)
	v_pk_fma_f32 v[18:19], v[16:17], v[74:75], v[86:87]
	v_pk_fma_f32 v[16:17], v[76:77], v[78:79], v[88:89]
	v_mul_f32_e32 v76, v19, v103
	v_mul_f32_e32 v77, v18, v106
	v_fmac_f32_e32 v76, v18, v102
	v_fmac_f32_e32 v77, v19, v107
	v_fmac_f32_e32 v76, v16, v104
	v_fmac_f32_e32 v77, v16, v108
	v_cvt_pk_bf16_f32 v74, v18, v19
	v_cvt_pk_bf16_f32 v75, v16, v17
	v_fmac_f32_e32 v76, v17, v105
	v_fmac_f32_e32 v77, v17, v109
	global_store_dwordx2 v[126:127], v[74:75], off offset:1536
	v_add_f32_e32 v74, v69, v76
	v_add_f32_e32 v69, v77, v90
	ds_read_b128 v[168:171], v36 offset:8192
	ds_read_b128 v[172:175], v36 offset:9216
	ds_read_b128 v[176:179], v36 offset:10240
	ds_read_b128 v[180:183], v36 offset:11264
	ds_read_b128 v[184:187], v36 offset:12288
	ds_read_b128 v[188:191], v36 offset:13312
	ds_read_b128 v[192:195], v36 offset:14336
	ds_read_b128 v[196:199], v36 offset:15360
	ds_read_b128 v[200:203], v36 offset:16384
	ds_read_b128 v[204:207], v36 offset:17408
	ds_read_b128 v[208:211], v36 offset:18432
	ds_read_b128 v[212:215], v36 offset:19456
	s_waitcnt lgkmcnt(8)
	v_pk_mul_f32 v[216:217], v[28:29], v[168:169]
	v_pk_fma_f32 v[216:217], v[30:31], v[170:171], v[216:217]
	v_pk_fma_f32 v[216:217], v[26:27], v[172:173], v[216:217]
	v_pk_fma_f32 v[216:217], v[24:25], v[174:175], v[216:217]
	v_pk_fma_f32 v[216:217], v[22:23], v[176:177], v[216:217]
	v_pk_fma_f32 v[216:217], v[20:21], v[178:179], v[216:217]
	v_pk_fma_f32 v[216:217], v[18:19], v[180:181], v[216:217]
	v_pk_fma_f32 v[216:217], v[16:17], v[182:183], v[216:217]
	ds_read_b128 v[168:171], v36 offset:20480
	ds_read_b128 v[172:175], v36 offset:21504
	ds_read_b128 v[176:179], v36 offset:22528
	ds_read_b128 v[180:183], v36 offset:23552
	v_add_f32_e32 v75, v216, v217
	s_waitcnt lgkmcnt(8)
	v_pk_mul_f32 v[216:217], v[28:29], v[184:185]
	v_pk_fma_f32 v[216:217], v[30:31], v[186:187], v[216:217]
	v_pk_fma_f32 v[216:217], v[26:27], v[188:189], v[216:217]
	v_pk_fma_f32 v[216:217], v[24:25], v[190:191], v[216:217]
	v_pk_fma_f32 v[216:217], v[22:23], v[192:193], v[216:217]
	v_pk_fma_f32 v[216:217], v[20:21], v[194:195], v[216:217]
	v_pk_fma_f32 v[216:217], v[18:19], v[196:197], v[216:217]
	v_pk_fma_f32 v[216:217], v[16:17], v[198:199], v[216:217]
	ds_read_b128 v[184:187], v36 offset:24576
	ds_read_b128 v[188:191], v36 offset:25600
	ds_read_b128 v[192:195], v36 offset:26624
	ds_read_b128 v[196:199], v36 offset:27648
	v_add_f32_e32 v76, v216, v217
	s_waitcnt lgkmcnt(8)
	v_pk_mul_f32 v[216:217], v[28:29], v[200:201]
	v_pk_fma_f32 v[216:217], v[30:31], v[202:203], v[216:217]
	v_pk_fma_f32 v[216:217], v[26:27], v[204:205], v[216:217]
	v_pk_fma_f32 v[216:217], v[24:25], v[206:207], v[216:217]
	v_pk_fma_f32 v[216:217], v[22:23], v[208:209], v[216:217]
	v_pk_fma_f32 v[216:217], v[20:21], v[210:211], v[216:217]
	v_pk_fma_f32 v[216:217], v[18:19], v[212:213], v[216:217]
	v_pk_fma_f32 v[216:217], v[16:17], v[214:215], v[216:217]
	ds_read_b128 v[200:203], v36 offset:28672
	ds_read_b128 v[204:207], v36 offset:29696
	ds_read_b128 v[208:211], v36 offset:30720
	ds_read_b128 v[212:215], v36 offset:31744
	v_add_f32_e32 v77, v216, v217
	s_waitcnt lgkmcnt(8)
	v_pk_mul_f32 v[216:217], v[28:29], v[168:169]
	v_pk_fma_f32 v[216:217], v[30:31], v[170:171], v[216:217]
	v_pk_fma_f32 v[216:217], v[26:27], v[172:173], v[216:217]
	v_pk_fma_f32 v[216:217], v[24:25], v[174:175], v[216:217]
	v_pk_fma_f32 v[216:217], v[22:23], v[176:177], v[216:217]
	v_pk_fma_f32 v[216:217], v[20:21], v[178:179], v[216:217]
	v_pk_fma_f32 v[216:217], v[18:19], v[180:181], v[216:217]
	v_pk_fma_f32 v[216:217], v[16:17], v[182:183], v[216:217]
	ds_read_b128 v[168:171], v36 offset:32768
	ds_read_b128 v[172:175], v36 offset:33792
	ds_read_b128 v[176:179], v36 offset:34816
	ds_read_b128 v[180:183], v36 offset:35840
	v_add_f32_e32 v94, v216, v217
	s_waitcnt lgkmcnt(8)
	v_pk_mul_f32 v[216:217], v[28:29], v[184:185]
	v_pk_fma_f32 v[216:217], v[30:31], v[186:187], v[216:217]
	v_pk_fma_f32 v[216:217], v[26:27], v[188:189], v[216:217]
	v_pk_fma_f32 v[216:217], v[24:25], v[190:191], v[216:217]
	v_pk_fma_f32 v[216:217], v[22:23], v[192:193], v[216:217]
	v_pk_fma_f32 v[216:217], v[20:21], v[194:195], v[216:217]
	v_pk_fma_f32 v[216:217], v[18:19], v[196:197], v[216:217]
	v_pk_fma_f32 v[216:217], v[16:17], v[198:199], v[216:217]
	ds_read_b128 v[184:187], v36 offset:36864
	ds_read_b128 v[188:191], v36 offset:37888
	ds_read_b128 v[192:195], v36 offset:38912
	ds_read_b128 v[196:199], v36 offset:39936
	v_add_f32_e32 v95, v216, v217
	s_waitcnt lgkmcnt(8)
	v_pk_mul_f32 v[216:217], v[28:29], v[200:201]
	v_pk_fma_f32 v[216:217], v[30:31], v[202:203], v[216:217]
	v_pk_fma_f32 v[216:217], v[26:27], v[204:205], v[216:217]
	v_pk_fma_f32 v[216:217], v[24:25], v[206:207], v[216:217]
	v_pk_fma_f32 v[216:217], v[22:23], v[208:209], v[216:217]
	v_pk_fma_f32 v[216:217], v[20:21], v[210:211], v[216:217]
	v_pk_fma_f32 v[216:217], v[18:19], v[212:213], v[216:217]
	v_pk_fma_f32 v[216:217], v[16:17], v[214:215], v[216:217]
	ds_read_b128 v[200:203], v36 offset:40960
	ds_read_b128 v[204:207], v36 offset:41984
	ds_read_b128 v[208:211], v36 offset:43008
	ds_read_b128 v[212:215], v36 offset:44032
	v_add_f32_e32 v96, v216, v217
	s_waitcnt lgkmcnt(8)
	v_pk_mul_f32 v[216:217], v[28:29], v[168:169]
	v_pk_fma_f32 v[216:217], v[30:31], v[170:171], v[216:217]
	v_pk_fma_f32 v[216:217], v[26:27], v[172:173], v[216:217]
	v_pk_fma_f32 v[216:217], v[24:25], v[174:175], v[216:217]
	v_pk_fma_f32 v[216:217], v[22:23], v[176:177], v[216:217]
	v_pk_fma_f32 v[216:217], v[20:21], v[178:179], v[216:217]
	v_pk_fma_f32 v[216:217], v[18:19], v[180:181], v[216:217]
	v_pk_fma_f32 v[216:217], v[16:17], v[182:183], v[216:217]
	ds_read_b128 v[168:171], v36 offset:45056
	ds_read_b128 v[172:175], v36 offset:46080
	ds_read_b128 v[176:179], v36 offset:47104
	ds_read_b128 v[180:183], v36 offset:48128
	v_add_f32_e32 v97, v216, v217
	s_waitcnt lgkmcnt(8)
	v_pk_mul_f32 v[216:217], v[28:29], v[184:185]
	v_pk_fma_f32 v[216:217], v[30:31], v[186:187], v[216:217]
	v_pk_fma_f32 v[216:217], v[26:27], v[188:189], v[216:217]
	v_pk_fma_f32 v[216:217], v[24:25], v[190:191], v[216:217]
	v_pk_fma_f32 v[216:217], v[22:23], v[192:193], v[216:217]
	v_pk_fma_f32 v[216:217], v[20:21], v[194:195], v[216:217]
	v_pk_fma_f32 v[216:217], v[18:19], v[196:197], v[216:217]
	v_pk_fma_f32 v[216:217], v[16:17], v[198:199], v[216:217]
	ds_read_b128 v[184:187], v36 offset:49152
	ds_read_b128 v[188:191], v36 offset:50176
	ds_read_b128 v[192:195], v36 offset:51200
	ds_read_b128 v[196:199], v36 offset:52224
	v_add_f32_e32 v98, v216, v217
	s_waitcnt lgkmcnt(8)
	v_pk_mul_f32 v[216:217], v[28:29], v[200:201]
	v_pk_fma_f32 v[216:217], v[30:31], v[202:203], v[216:217]
	v_pk_fma_f32 v[216:217], v[26:27], v[204:205], v[216:217]
	v_pk_fma_f32 v[216:217], v[24:25], v[206:207], v[216:217]
	v_pk_fma_f32 v[216:217], v[22:23], v[208:209], v[216:217]
	v_pk_fma_f32 v[216:217], v[20:21], v[210:211], v[216:217]
	v_pk_fma_f32 v[216:217], v[18:19], v[212:213], v[216:217]
	v_pk_fma_f32 v[216:217], v[16:17], v[214:215], v[216:217]
	ds_read_b128 v[200:203], v36 offset:53248
	ds_read_b128 v[204:207], v36 offset:54272
	ds_read_b128 v[208:211], v36 offset:55296
	ds_read_b128 v[212:215], v36 offset:56320
	v_add_f32_e32 v99, v216, v217
	s_waitcnt lgkmcnt(8)
	v_pk_mul_f32 v[216:217], v[28:29], v[168:169]
	v_pk_fma_f32 v[216:217], v[30:31], v[170:171], v[216:217]
	v_pk_fma_f32 v[216:217], v[26:27], v[172:173], v[216:217]
	v_pk_fma_f32 v[216:217], v[24:25], v[174:175], v[216:217]
	v_pk_fma_f32 v[216:217], v[22:23], v[176:177], v[216:217]
	v_pk_fma_f32 v[216:217], v[20:21], v[178:179], v[216:217]
	v_pk_fma_f32 v[216:217], v[18:19], v[180:181], v[216:217]
	v_pk_fma_f32 v[216:217], v[16:17], v[182:183], v[216:217]
	ds_read_b128 v[168:171], v36 offset:57344
	ds_read_b128 v[172:175], v36 offset:58368
	ds_read_b128 v[176:179], v36 offset:59392
	ds_read_b128 v[180:183], v36 offset:60416
	v_add_f32_e32 v100, v216, v217
	s_waitcnt lgkmcnt(8)
	v_pk_mul_f32 v[216:217], v[28:29], v[184:185]
	v_pk_fma_f32 v[216:217], v[30:31], v[186:187], v[216:217]
	v_pk_fma_f32 v[216:217], v[26:27], v[188:189], v[216:217]
	v_pk_fma_f32 v[216:217], v[24:25], v[190:191], v[216:217]
	v_pk_fma_f32 v[216:217], v[22:23], v[192:193], v[216:217]
	v_pk_fma_f32 v[216:217], v[20:21], v[194:195], v[216:217]
	v_pk_fma_f32 v[216:217], v[18:19], v[196:197], v[216:217]
	v_pk_fma_f32 v[216:217], v[16:17], v[198:199], v[216:217]
	ds_read_b128 v[184:187], v36 offset:61440
	ds_read_b128 v[188:191], v36 offset:62464
	ds_read_b128 v[192:195], v36 offset:63488
	ds_read_b128 v[196:199], v36 offset:64512
	v_add_f32_e32 v101, v216, v217
	s_waitcnt lgkmcnt(8)
	v_pk_mul_f32 v[216:217], v[28:29], v[200:201]
	v_pk_fma_f32 v[216:217], v[30:31], v[202:203], v[216:217]
	v_pk_fma_f32 v[216:217], v[26:27], v[204:205], v[216:217]
	v_pk_fma_f32 v[216:217], v[24:25], v[206:207], v[216:217]
	v_pk_fma_f32 v[216:217], v[22:23], v[208:209], v[216:217]
	v_pk_fma_f32 v[216:217], v[20:21], v[210:211], v[216:217]
	v_pk_fma_f32 v[216:217], v[18:19], v[212:213], v[216:217]
	v_pk_fma_f32 v[216:217], v[16:17], v[214:215], v[216:217]
	v_add_f32_e32 v102, v216, v217
	s_waitcnt lgkmcnt(4)
	v_pk_mul_f32 v[216:217], v[28:29], v[168:169]
	v_pk_fma_f32 v[216:217], v[30:31], v[170:171], v[216:217]
	v_pk_fma_f32 v[216:217], v[26:27], v[172:173], v[216:217]
	v_pk_fma_f32 v[216:217], v[24:25], v[174:175], v[216:217]
	v_pk_fma_f32 v[216:217], v[22:23], v[176:177], v[216:217]
	v_pk_fma_f32 v[216:217], v[20:21], v[178:179], v[216:217]
	v_pk_fma_f32 v[216:217], v[18:19], v[180:181], v[216:217]
	v_pk_fma_f32 v[216:217], v[16:17], v[182:183], v[216:217]
	v_add_f32_e32 v103, v216, v217
	s_waitcnt lgkmcnt(0)
	v_pk_mul_f32 v[216:217], v[28:29], v[184:185]
	v_pk_fma_f32 v[216:217], v[30:31], v[186:187], v[216:217]
	v_pk_fma_f32 v[216:217], v[26:27], v[188:189], v[216:217]
	v_pk_fma_f32 v[216:217], v[24:25], v[190:191], v[216:217]
	v_pk_fma_f32 v[216:217], v[22:23], v[192:193], v[216:217]
	v_pk_fma_f32 v[216:217], v[20:21], v[194:195], v[216:217]
	v_pk_fma_f32 v[216:217], v[18:19], v[196:197], v[216:217]
	v_pk_fma_f32 v[216:217], v[16:17], v[198:199], v[216:217]
	v_add_f32_e32 v16, v216, v217
	v_cndmask_b32_e64 v18, v74, v97, s[0:1]
	v_mov_b32_e32 v19, v18
	s_nop 1
	v_permlane32_swap_b32_e32 v18, v19
	v_cndmask_b32_e64 v18, v18, v19, s[0:1]
	v_cndmask_b32_e64 v19, v69, v98, s[0:1]
	v_mov_b32_e32 v20, v19
	s_nop 1
	v_permlane32_swap_b32_e32 v19, v20
	v_cndmask_b32_e64 v19, v19, v20, s[0:1]
	v_cndmask_b32_e64 v20, v75, v99, s[0:1]
	v_mov_b32_e32 v21, v20
	s_nop 1
	v_permlane32_swap_b32_e32 v20, v21
	v_cndmask_b32_e64 v20, v20, v21, s[0:1]
	v_cndmask_b32_e64 v21, v76, v100, s[0:1]
	v_mov_b32_e32 v22, v21
	s_nop 1
	v_permlane32_swap_b32_e32 v21, v22
	v_cndmask_b32_e64 v21, v21, v22, s[0:1]
	v_cndmask_b32_e64 v22, v77, v101, s[0:1]
	v_mov_b32_e32 v23, v22
	s_nop 1
	v_permlane32_swap_b32_e32 v22, v23
	v_cndmask_b32_e64 v17, v97, v74, s[0:1]
	v_cndmask_b32_e64 v22, v22, v23, s[0:1]
	v_cndmask_b32_e64 v23, v94, v102, s[0:1]
	v_add_f32_e32 v17, v17, v18
	v_cndmask_b32_e64 v18, v98, v69, s[0:1]
	v_mov_b32_e32 v24, v23
	v_add_f32_e32 v18, v18, v19
	v_cndmask_b32_e64 v19, v99, v75, s[0:1]
	v_permlane32_swap_b32_e32 v23, v24
	v_add_f32_e32 v19, v19, v20
	v_cndmask_b32_e64 v20, v100, v76, s[0:1]
	v_cndmask_b32_e64 v23, v23, v24, s[0:1]
	v_cndmask_b32_e64 v24, v95, v103, s[0:1]
	v_add_f32_e32 v20, v20, v21
	v_cndmask_b32_e64 v21, v101, v77, s[0:1]
	v_mov_b32_e32 v25, v24
	v_add_f32_e32 v21, v21, v22
	v_cndmask_b32_e64 v22, v102, v94, s[0:1]
	v_permlane32_swap_b32_e32 v24, v25
	v_add_f32_e32 v22, v22, v23
	v_cndmask_b32_e64 v23, v103, v95, s[0:1]
	v_cndmask_b32_e64 v24, v24, v25, s[0:1]
	v_add_f32_e32 v23, v23, v24
	v_cndmask_b32_e64 v24, v16, v96, s[0:1]
	v_cndmask_b32_e64 v16, v96, v16, s[0:1]
	v_mov_b32_e32 v25, v16
	s_nop 1
	v_permlane32_swap_b32_e32 v16, v25
	v_cndmask_b32_e64 v16, v16, v25, s[0:1]
	v_add_f32_e32 v16, v24, v16
	v_cndmask_b32_e64 v24, v21, v17, s[16:17]
	v_cndmask_b32_e64 v17, v17, v21, s[16:17]
	v_mov_b32_e32 v21, v17
	s_nop 1
	v_permlane16_swap_b32_e32 v17, v21
	v_cndmask_b32_e64 v17, v17, v21, s[16:17]
	v_cndmask_b32_e64 v21, v22, v18, s[16:17]
	v_cndmask_b32_e64 v18, v18, v22, s[16:17]
	v_mov_b32_e32 v22, v18
	s_nop 1
	v_permlane16_swap_b32_e32 v18, v22
	v_cndmask_b32_e64 v18, v18, v22, s[16:17]
	v_add_f32_e32 v18, v21, v18
	v_cndmask_b32_e64 v21, v23, v19, s[16:17]
	v_cndmask_b32_e64 v19, v19, v23, s[16:17]
	v_mov_b32_e32 v22, v19
	s_nop 1
	v_permlane16_swap_b32_e32 v19, v22
	v_cndmask_b32_e64 v19, v19, v22, s[16:17]
	v_add_f32_e32 v19, v21, v19
	v_cndmask_b32_e64 v21, v16, v20, s[16:17]
	v_cndmask_b32_e64 v16, v20, v16, s[16:17]
	v_mov_b32_e32 v20, v16
	s_nop 1
	v_permlane16_swap_b32_e32 v16, v20
	v_cndmask_b32_e64 v16, v16, v20, s[16:17]
	v_add_f32_e32 v17, v24, v17
	v_add_f32_e32 v16, v21, v16
	v_cndmask_b32_e64 v20, v17, v19, s[4:5]
	v_cndmask_b32_e64 v21, v18, v16, s[4:5]
	ds_bpermute_b32 v20, v70, v20
	ds_bpermute_b32 v21, v70, v21
	v_cndmask_b32_e64 v17, v19, v17, s[4:5]
	v_cndmask_b32_e64 v16, v16, v18, s[4:5]
	s_waitcnt lgkmcnt(1)
	v_add_f32_e32 v17, v17, v20
	s_waitcnt lgkmcnt(0)
	v_add_f32_e32 v16, v16, v21
	v_cndmask_b32_e64 v18, v17, v16, s[6:7]
	ds_bpermute_b32 v18, v71, v18
	v_cndmask_b32_e64 v16, v16, v17, s[6:7]
	s_waitcnt lgkmcnt(0)
	v_add_f32_e32 v16, v16, v18
	ds_bpermute_b32 v17, v72, v16
	s_waitcnt lgkmcnt(0)
	v_add_f32_e32 v16, v16, v17
	ds_bpermute_b32 v17, v73, v16
	s_waitcnt lgkmcnt(0)
	v_add_f32_e32 v16, v16, v17
	ds_bpermute_b32 v17, v70, v16
	s_waitcnt lgkmcnt(0)
	v_max_f32_e32 v17, v17, v17
	v_max_f32_e32 v17, v16, v17
	ds_bpermute_b32 v18, v71, v17
	s_waitcnt lgkmcnt(0)
	v_max_f32_e32 v18, v18, v18
	v_max_f32_e32 v17, v17, v18
	v_mov_b32_e32 v18, v17
	s_nop 1
	v_permlane16_swap_b32_e32 v17, v18
	v_max_f32_e32 v18, v18, v18
	v_max_f32_e32 v17, v17, v17
	v_max_f32_e32 v17, v17, v18
	v_mov_b32_e32 v18, v17
	s_nop 1
	v_permlane32_swap_b32_e32 v17, v18
	v_max_f32_e32 v18, v18, v18
	v_max_f32_e32 v17, v17, v17
	v_max_f32_e32 v17, v17, v18
	v_sub_f32_e32 v16, v16, v17
	v_mul_f32_e32 v17, 0x3fb8aa3b, v16
	v_fma_f32 v18, v16, s34, -v17
	v_rndne_f32_e32 v19, v17
	v_fmac_f32_e32 v18, 0x32a5705f, v16
	v_sub_f32_e32 v17, v17, v19
	v_add_f32_e32 v17, v17, v18
	v_exp_f32_e32 v17, v17
	v_cvt_i32_f32_e32 v18, v19
	v_cmp_ngt_f32_e32 vcc, s35, v16
	v_ldexp_f32 v17, v17, v18
	s_nop 0
	v_cndmask_b32_e32 v17, 0, v17, vcc
	v_cmp_nlt_f32_e32 vcc, s36, v16
	s_nop 1
	v_cndmask_b32_e32 v16, v37, v17, vcc
	ds_bpermute_b32 v17, v70, v16
	s_waitcnt lgkmcnt(0)
	v_add_f32_e32 v17, v16, v17
	ds_bpermute_b32 v18, v71, v17
	s_waitcnt lgkmcnt(0)
	v_add_f32_e32 v17, v17, v18
	v_mov_b32_e32 v18, v17
	s_nop 1
	v_permlane16_swap_b32_e32 v17, v18
	v_add_f32_e32 v17, v17, v18
	v_mov_b32_e32 v18, v17
	s_nop 1
	v_permlane32_swap_b32_e32 v17, v18
	s_and_saveexec_b64 s[2:3], s[8:9]
	s_cbranch_execz .LBB0_1873
	v_add_f32_e32 v17, v17, v18
	v_div_scale_f32 v18, s[18:19], v17, v17, v16
	v_rcp_f32_e32 v19, v18
	v_div_scale_f32 v20, vcc, v16, v17, v16
	v_fma_f32 v21, -v18, v19, 1.0
	v_fmac_f32_e32 v19, v21, v19
	v_mul_f32_e32 v21, v20, v19
	v_fma_f32 v22, -v18, v21, v20
	v_fmac_f32_e32 v21, v22, v19
	v_fma_f32 v18, -v18, v21, v20
	v_div_fmas_f32 v18, v18, v19, v21
	v_div_fixup_f32 v18, v18, v17, v16
	v_lshlrev_b64 v[16:17], 6, v[32:33]
	v_lshl_add_u64 v[16:17], v[56:57], 0, v[16:17]
	global_store_dword v[16:17], v18, off
